# no initial cg grid.sync; write-through stores in row-pass/prep phases; DQ128 attention: waves 4-7 issue their K/V LDS-DMA mid-step instead of at step start
# speedup vs baseline: 1.0078x; 1.0033x over previous
; #define PK8(P, BASE, OUT) do { u32x4 w = {cvtpk(P[BASE + 0], P[BASE + 1]), cvtpk(P[BASE + 2], P[BASE + 3]), cvtpk(P[BASE + 4], P[BASE + 5]), cvtpk(P[BASE + 6], P[BASE + 7])}; \
;     OUT = *reinterpret_cast<bf16x8*>(&w); } while (0)
; __device__ __forceinline__ void finishSM(f32x16& p0, f32x16& p1, float alpha, float& l_reg, bf16x8& pa0, bf16x8& pa1, bf16x8& pa2, bf16x8& pa3) {
; #pragma unroll
;   for (int r = 0; r < 16; ++r) p1[r] = __builtin_amdgcn_exp2f(p1[r]);
;   float ps = 0;
; #pragma unroll
;   for (int r = 0; r < 16; ++r) ps += p0[r];
; #pragma unroll
;   for (int r = 0; r < 16; ++r) ps += p1[r];
;   { auto rr = __builtin_amdgcn_permlane32_swap(__float_as_uint(ps), __float_as_uint(ps), false, false);
;     ps = __uint_as_float(rr[0]) + __uint_as_float(rr[1]); }
;   l_reg = l_reg * alpha + ps;
;     ...
;   PK8(p0, 0, pa0); PK8(p0, 8, pa1); PK8(p1, 0, pa2); PK8(p1, 8, pa3);
;     ...
; }
; template <int DQ, int MODE>
; __device__ __forceinline__ void attn_unit(const Args& a, char* lds, const int wave0) {
;     ...
;   f32x16 pA0, pA1, pB0, pB1; float mnA, mnB, alA, alB; bf16x8 pa0, pa1, pa2, pa3; const int NT = a.NT;
.LBB0_771:
	s_mul_hi_u32 s4, s4, 0xaaaaaaab
	s_lshr_b32 s4, s4, 1
	s_mul_i32 s4, s4, 0xc000
	s_mul_hi_u32 s5, s64, 0xaaaaaaab
	v_subrev_u32_e32 v96, s4, v186
	s_add_i32 s4, s47, 1
	s_lshr_b32 s5, s5, 1
	s_mul_i32 s5, s5, 0xc000
	s_cmp_lt_u32 s4, 4
	v_subrev_u32_e32 v193, s5, v187
	s_cselect_b32 s5, 0, -4
	s_cselect_b32 s6, s20, s63
	s_add_i32 s5, s5, s47
	s_lshl_b32 s5, s5, 6
	s_add_i32 s5, s5, s6
	s_add_i32 s6, s5, 64
	s_cmp_lg_u32 0, -1
	s_mul_i32 s40, s6, 0x1600
	s_cselect_b32 s5, 0, 0
	s_mul_hi_i32 s9, s6, 0x1600
	s_add_u32 s6, s21, s40
	s_addc_u32 s7, s43, s9
	s_waitcnt vmcnt(0) lgkmcnt(0)
	s_barrier
	v_add_u32_e32 v233, s5, v96
	s_cmp_lt_u32 s93, 0x100
	s_cbranch_scc0 .Ldma1_skip_128
	v_readfirstlane_b32 s8, v180
	v_lshl_add_u64 v[96:97], v[162:163], 1, s[6:7]
	s_mov_b32 s41, m0
	s_mov_b32 m0, s8
	s_nop 0
	global_load_lds_dwordx4 v[96:97], off
	s_mov_b32 m0, s41
	v_lshl_add_u64 v[96:97], v[164:165], 1, s[6:7]
	s_add_i32 s6, s8, 0x400
	s_mov_b32 s7, m0
	s_mov_b32 m0, s6
	s_nop 0
	global_load_lds_dwordx4 v[96:97], off
	s_mov_b32 m0, s7
	s_add_u32 s6, s44, s40
	s_addc_u32 s7, s45, s9
	v_readfirstlane_b32 s8, v233
	v_lshl_add_u64 v[96:97], v[166:167], 1, s[6:7]
	s_mov_b32 s6, m0
	s_mov_b32 m0, s8
	s_nop 0
	global_load_lds_dwordx4 v[96:97], off
	s_mov_b32 m0, s6
	v_lshl_add_u64 v[96:97], v[96:97], 0, s[22:23]
	s_add_i32 s6, s8, 0x400
	s_mov_b32 s7, m0
	s_mov_b32 m0, s6
	s_nop 0
	global_load_lds_dwordx4 v[96:97], off
	s_mov_b32 m0, s7
.Ldma1_skip_128:
	ds_read_b128 v[220:223], v176 offset:24576
	ds_read_b128 v[96:99], v176 offset:16384
	v_exp_f32_e32 v197, v80
	v_add_f32_e32 v80, 0, v218
	v_add_f32_e32 v80, v219, v80
	v_add_f32_e32 v80, v215, v80
	s_waitcnt lgkmcnt(0)
	v_mfma_f32_32x32x16_bf16 v[112:127], v[96:99], v[144:147], v[64:79]
	v_add_f32_e32 v80, v217, v80
	v_add_f32_e32 v80, v213, v80
	v_add_f32_e32 v80, v216, v80
	v_add_f32_e32 v80, v212, v80
	v_add_f32_e32 v80, v214, v80
	v_add_f32_e32 v80, v208, v80
	v_add_f32_e32 v80, v210, v80
	v_mfma_f32_32x32x16_bf16 v[96:111], v[220:223], v[144:147], v[64:79]
	ds_read_b128 v[220:223], v181 offset:24576
	ds_read_b128 v[224:227], v181 offset:16384
	v_add_f32_e32 v80, v206, v80
	v_add_f32_e32 v80, v209, v80
	v_add_f32_e32 v80, v204, v80
	v_exp_f32_e32 v202, v81
	v_add_f32_e32 v80, v207, v80
	v_add_f32_e32 v80, v203, v80
	s_waitcnt lgkmcnt(1)
	v_mfma_f32_32x32x16_bf16 v[96:111], v[220:223], v[152:155], v[96:111]
	v_add_f32_e32 v80, v205, v80
	v_add_f32_e32 v80, v197, v80
	v_add_f32_e32 v80, v202, v80
	v_exp_f32_e32 v228, v90
	v_exp_f32_e32 v229, v91
	v_exp_f32_e32 v230, v92
	v_exp_f32_e32 v231, v93
	s_waitcnt lgkmcnt(0)
	v_mfma_f32_32x32x16_bf16 v[112:127], v[224:227], v[152:155], v[112:127]
	ds_read_b128 v[220:223], v178 offset:24576
	ds_read_b128 v[224:227], v178 offset:16384
	v_exp_f32_e32 v232, v94
	v_exp_f32_e32 v95, v95
	s_waitcnt lgkmcnt(1)
	v_mfma_f32_32x32x16_bf16 v[96:111], v[220:223], v[148:151], v[96:111]
	s_waitcnt lgkmcnt(0)
	v_mfma_f32_32x32x16_bf16 v[112:127], v[224:227], v[148:151], v[112:127]
	ds_read_b128 v[220:223], v177 offset:24576
	ds_read_b128 v[224:227], v177 offset:16384
	s_waitcnt lgkmcnt(1)
	v_mfma_f32_32x32x16_bf16 v[96:111], v[220:223], v[156:159], v[96:111]
	s_waitcnt lgkmcnt(0)
	v_mfma_f32_32x32x16_bf16 v[112:127], v[224:227], v[156:159], v[112:127]
	ds_read_b128 v[220:223], v176 offset:24704
	ds_read_b128 v[224:227], v176 offset:16512
	s_waitcnt lgkmcnt(1)
	v_mfma_f32_32x32x16_bf16 v[96:111], v[220:223], v[140:143], v[96:111]
	s_waitcnt lgkmcnt(0)
	v_mfma_f32_32x32x16_bf16 v[112:127], v[224:227], v[140:143], v[112:127]
	ds_read_b128 v[220:223], v181 offset:24704
	ds_read_b128 v[224:227], v181 offset:16512
	s_waitcnt lgkmcnt(1)
	v_mfma_f32_32x32x16_bf16 v[96:111], v[220:223], v[132:135], v[96:111]
	s_waitcnt lgkmcnt(0)
	v_mfma_f32_32x32x16_bf16 v[112:127], v[224:227], v[132:135], v[112:127]
	ds_read_b128 v[220:223], v178 offset:24704
	ds_read_b128 v[224:227], v178 offset:16512
	s_waitcnt lgkmcnt(1)
	v_mfma_f32_32x32x16_bf16 v[96:111], v[220:223], v[136:139], v[96:111]
	s_waitcnt lgkmcnt(0)
	v_mfma_f32_32x32x16_bf16 v[112:127], v[224:227], v[136:139], v[112:127]
	ds_read_b128 v[220:223], v177 offset:24704
	ds_read_b128 v[224:227], v177 offset:16512
	s_waitcnt lgkmcnt(1)
	v_mfma_f32_32x32x16_bf16 v[96:111], v[220:223], v[128:131], v[96:111]
	v_exp_f32_e32 v220, v82
	v_exp_f32_e32 v221, v83
	v_exp_f32_e32 v222, v84
	v_exp_f32_e32 v223, v85
	v_add_f32_e32 v80, v220, v80
	v_add_f32_e32 v80, v221, v80
	v_add_f32_e32 v80, v222, v80
	s_waitcnt lgkmcnt(0)
	v_mfma_f32_32x32x16_bf16 v[112:127], v[224:227], v[128:131], v[112:127]
	v_exp_f32_e32 v224, v86
	v_exp_f32_e32 v225, v87
	v_exp_f32_e32 v226, v88
	v_exp_f32_e32 v227, v89
	v_add_f32_e32 v80, v223, v80
	v_add_f32_e32 v80, v224, v80
	v_add_f32_e32 v80, v225, v80
	v_add_f32_e32 v80, v226, v80
	v_add_f32_e32 v80, v227, v80
	v_add_f32_e32 v80, v228, v80
	v_add_f32_e32 v80, v229, v80
	v_add_f32_e32 v80, v230, v80
	v_add_f32_e32 v80, v231, v80
	v_add_f32_e32 v80, v232, v80
	v_add_f32_e32 v191, v95, v80
	v_mov_b32_e32 v192, v191
	s_nop 1
	v_permlane32_swap_b32_e32 v191, v192
	v_cvt_pk_bf16_f32 v80, v218, v219
	v_cvt_pk_bf16_f32 v81, v215, v217
	v_cvt_pk_bf16_f32 v82, v213, v216
	v_cvt_pk_bf16_f32 v83, v212, v214
	v_cvt_pk_bf16_f32 v84, v208, v210
	v_cvt_pk_bf16_f32 v85, v206, v209
	v_cvt_pk_bf16_f32 v86, v204, v207
	v_cvt_pk_bf16_f32 v87, v203, v205
	v_cvt_pk_bf16_f32 v88, v197, v202
	v_cvt_pk_bf16_f32 v89, v220, v221
	v_cvt_pk_bf16_f32 v90, v222, v223
	v_cvt_pk_bf16_f32 v91, v224, v225
	v_cvt_pk_bf16_f32 v92, v226, v227
	v_cvt_pk_bf16_f32 v93, v228, v229
	v_cvt_pk_bf16_f32 v94, v230, v231
	v_cvt_pk_bf16_f32 v95, v232, v95
	s_cmp_lt_u32 s93, 0x100
	s_cbranch_scc1 .Ldma1b_skip_128
	v_readfirstlane_b32 s8, v180
	v_lshl_add_u64 v[246:247], v[162:163], 1, s[6:7]
	s_mov_b32 m0, s8
	s_nop 0
	global_load_lds_dwordx4 v[246:247], off
	v_lshl_add_u64 v[246:247], v[164:165], 1, s[6:7]
	s_add_i32 s6, s8, 0x400
	s_mov_b32 m0, s6
	s_nop 0
	global_load_lds_dwordx4 v[246:247], off
	s_add_u32 s6, s44, s40
	s_addc_u32 s7, s45, s9
	v_readfirstlane_b32 s8, v233
	v_lshl_add_u64 v[246:247], v[166:167], 1, s[6:7]
	s_mov_b32 m0, s8
	s_nop 0
	global_load_lds_dwordx4 v[246:247], off
	v_lshl_add_u64 v[246:247], v[246:247], 0, s[22:23]
	s_add_i32 s6, s8, 0x400
	s_mov_b32 m0, s6
	s_nop 0
	global_load_lds_dwordx4 v[246:247], off
; #define SBAR() __builtin_amdgcn_sched_barrier(0)
; template <bool FIRST> __device__ __forceinline__ void partialSM(f32x16& p0, f32x16& p1, float& m_reg, float& alpha, f32x16& negm, const float thr) {
;   float pmax = p0[0];
; #pragma unroll
;   for (int r = 1; r < 16; ++r) pmax = fmaxf(pmax, p0[r]);
; #pragma unroll
;   for (int r = 0; r < 16; ++r) pmax = fmaxf(pmax, p1[r]);
;   { auto rr = __builtin_amdgcn_permlane32_swap(__float_as_uint(pmax), __float_as_uint(pmax), false, false);
;     pmax = fmaxf(__uint_as_float(rr[0]), __uint_as_float(rr[1])); }
;   alpha = 1.f;
;   if (FIRST || !__builtin_expect(__all(pmax <= thr), 1)) {
; template <int D0> __device__ __forceinline__ void pv_one(f32x16& od, int vb, bf16x8 pa0, bf16x8 pa1, bf16x8 pa2, bf16x8 pa3) {
;   const s16x4 l0 = tr_read<v_rd_off(D0, 0, 0)>(vb), h0 = tr_read<v_rd_off(D0, 0, 1)>(vb), l1 = tr_read<v_rd_off(D0, 1, 0)>(vb), h1 = tr_read<v_rd_off(D0, 1, 1)>(vb);
;   const s16x4 l2 = tr_read<v_rd_off(D0, 2, 0)>(vb), h2 = tr_read<v_rd_off(D0, 2, 1)>(vb), l3 = tr_read<v_rd_off(D0, 3, 0)>(vb), h3 = tr_read<v_rd_off(D0, 3, 1)>(vb);
;   asm volatile("s_waitcnt lgkmcnt(0)" ::: "memory"); SBAR();
;     ...
;   od = __builtin_amdgcn_mfma_f32_32x32x16_bf16(pa0, PK(l0, h0), od, 0, 0, 0);
;   od = __builtin_amdgcn_mfma_f32_32x32x16_bf16(pa1, PK(l1, h1), od, 0, 0, 0);
;   od = __builtin_amdgcn_mfma_f32_32x32x16_bf16(pa2, PK(l2, h2), od, 0, 0, 0);
;   od = __builtin_amdgcn_mfma_f32_32x32x16_bf16(pa3, PK(l3, h3), od, 0, 0, 0);
;     ...
; }
; __device__ __forceinline__ void pv_d0(f32x16* o, int vb, bf16x8 pa0, bf16x8 pa1, bf16x8 pa2, bf16x8 pa3) {
;   pv_one<0>(o[0], vb, pa0, pa1, pa2, pa3); pv_one<1>(o[1], vb, pa0, pa1, pa2, pa3); pv_one<2>(o[2], vb, pa0, pa1, pa2, pa3); pv_one<3>(o[3], vb, pa0, pa1, pa2, pa3);
; }
.Ldma1b_skip_128:
	v_add_u32_e32 v193, s5, v193
	ds_read_b64_tr_b16 v[202:203], v193 offset:0
	ds_read_b64_tr_b16 v[204:205], v193 offset:0x800
	ds_read_b64_tr_b16 v[206:207], v193 offset:0x1000
	ds_read_b64_tr_b16 v[208:209], v193 offset:0x1800
	ds_read_b64_tr_b16 v[212:213], v193 offset:0x2000
	ds_read_b64_tr_b16 v[214:215], v193 offset:0x2800
	ds_read_b64_tr_b16 v[216:217], v193 offset:0x3000
	ds_read_b64_tr_b16 v[218:219], v193 offset:0x3800
	s_waitcnt lgkmcnt(0)
	s_nop 0
	v_mfma_f32_32x32x16_bf16 v[0:15], v[80:83], v[202:205], v[0:15]
	ds_read_b64_tr_b16 v[202:203], v193 offset:0x200
	ds_read_b64_tr_b16 v[204:205], v193 offset:0xa00
	v_mfma_f32_32x32x16_bf16 v[0:15], v[84:87], v[206:209], v[0:15]
	ds_read_b64_tr_b16 v[206:207], v193 offset:0x1200
	ds_read_b64_tr_b16 v[208:209], v193 offset:0x1a00
	v_mfma_f32_32x32x16_bf16 v[0:15], v[88:91], v[212:215], v[0:15]
	ds_read_b64_tr_b16 v[212:213], v193 offset:0x2200
	ds_read_b64_tr_b16 v[214:215], v193 offset:0x2a00
	v_mfma_f32_32x32x16_bf16 v[0:15], v[92:95], v[216:219], v[0:15]
	ds_read_b64_tr_b16 v[216:217], v193 offset:0x3200
	ds_read_b64_tr_b16 v[218:219], v193 offset:0x3a00
	s_waitcnt lgkmcnt(0)
	v_mfma_f32_32x32x16_bf16 v[48:63], v[80:83], v[202:205], v[48:63]
	ds_read_b64_tr_b16 v[202:203], v193 offset:0x400
	ds_read_b64_tr_b16 v[204:205], v193 offset:0xc00
	v_mfma_f32_32x32x16_bf16 v[48:63], v[84:87], v[206:209], v[48:63]
	ds_read_b64_tr_b16 v[206:207], v193 offset:0x1400
	ds_read_b64_tr_b16 v[208:209], v193 offset:0x1c00
	v_mfma_f32_32x32x16_bf16 v[48:63], v[88:91], v[212:215], v[48:63]
	ds_read_b64_tr_b16 v[212:213], v193 offset:0x2400
	ds_read_b64_tr_b16 v[214:215], v193 offset:0x2c00
	v_mfma_f32_32x32x16_bf16 v[48:63], v[92:95], v[216:219], v[48:63]
	ds_read_b64_tr_b16 v[216:217], v193 offset:0x3400
	ds_read_b64_tr_b16 v[218:219], v193 offset:0x3c00
	s_waitcnt lgkmcnt(0)
	v_mfma_f32_32x32x16_bf16 v[32:47], v[80:83], v[202:205], v[32:47]
	ds_read_b64_tr_b16 v[202:203], v193 offset:0x600
	ds_read_b64_tr_b16 v[204:205], v193 offset:0xe00
	v_mfma_f32_32x32x16_bf16 v[32:47], v[84:87], v[206:209], v[32:47]
	ds_read_b64_tr_b16 v[206:207], v193 offset:0x1600
	ds_read_b64_tr_b16 v[208:209], v193 offset:0x1e00
	v_mfma_f32_32x32x16_bf16 v[32:47], v[88:91], v[212:215], v[32:47]
	ds_read_b64_tr_b16 v[212:213], v193 offset:0x2600
	ds_read_b64_tr_b16 v[214:215], v193 offset:0x2e00
	v_mfma_f32_32x32x16_bf16 v[32:47], v[92:95], v[216:219], v[32:47]
	ds_read_b64_tr_b16 v[216:217], v193 offset:0x3600
	ds_read_b64_tr_b16 v[218:219], v193 offset:0x3e00
	s_waitcnt lgkmcnt(0)
	v_mfma_f32_32x32x16_bf16 v[16:31], v[80:83], v[202:205], v[16:31]
	v_max_f32_e32 v80, v113, v113
	v_max_f32_e32 v81, v112, v112
	v_max_f32_e32 v80, v81, v80
	v_max3_f32 v80, v80, v114, v115
	v_max3_f32 v80, v80, v116, v117
	v_max3_f32 v80, v80, v118, v119
	v_max3_f32 v80, v80, v120, v121
	v_mfma_f32_32x32x16_bf16 v[16:31], v[84:87], v[206:209], v[16:31]
	v_max3_f32 v80, v80, v122, v123
	v_max3_f32 v80, v80, v124, v125
	v_max3_f32 v80, v80, v126, v127
	v_max3_f32 v80, v80, v96, v97
	v_max3_f32 v80, v80, v98, v99
	v_max3_f32 v80, v80, v100, v101
	v_max3_f32 v80, v80, v102, v103
	v_mfma_f32_32x32x16_bf16 v[16:31], v[88:91], v[212:215], v[16:31]
	v_max3_f32 v80, v80, v104, v105
	v_max3_f32 v80, v80, v106, v107
	v_max3_f32 v80, v80, v108, v109
	v_max3_f32 v80, v80, v110, v111
	v_mov_b32_e32 v81, v80
	s_nop 1
	v_permlane32_swap_b32_e32 v80, v81
	v_mfma_f32_32x32x16_bf16 v[16:31], v[92:95], v[216:219], v[16:31]
	v_max_f32_e32 v81, v81, v81
	v_max_f32_e32 v80, v80, v80
	v_max_f32_e32 v80, v80, v81
	v_cmp_ge_f32_e32 vcc, s81, v80
	s_cmp_eq_u64 vcc, exec
	s_cbranch_scc0 .LBB0_785
	v_mov_b32_e32 v202, 1.0
	v_cmp_gt_f32_e32 vcc, 1.0, v202
	s_cbranch_vccz .LBB0_776

; #define PK8(P, BASE, OUT) do { u32x4 w = {cvtpk(P[BASE + 0], P[BASE + 1]), cvtpk(P[BASE + 2], P[BASE + 3]), cvtpk(P[BASE + 4], P[BASE + 5]), cvtpk(P[BASE + 6], P[BASE + 7])}; \
;     OUT = *reinterpret_cast<bf16x8*>(&w); } while (0)
; __device__ __forceinline__ void finishSM(f32x16& p0, f32x16& p1, float alpha, float& l_reg, bf16x8& pa0, bf16x8& pa1, bf16x8& pa2, bf16x8& pa3) {
; #pragma unroll
;   for (int r = 0; r < 16; ++r) p1[r] = __builtin_amdgcn_exp2f(p1[r]);
;   float ps = 0;
; #pragma unroll
;   for (int r = 0; r < 16; ++r) ps += p0[r];
; #pragma unroll
;   for (int r = 0; r < 16; ++r) ps += p1[r];
;   { auto rr = __builtin_amdgcn_permlane32_swap(__float_as_uint(ps), __float_as_uint(ps), false, false);
;     ps = __uint_as_float(rr[0]) + __uint_as_float(rr[1]); }
;   l_reg = l_reg * alpha + ps;
;     ...
;   PK8(p0, 0, pa0); PK8(p0, 8, pa1); PK8(p1, 0, pa2); PK8(p1, 8, pa3);
;     ...
; }
; template <int DQ> __device__ __forceinline__ void qkt(f32x16& p0, f32x16& p1, const int (&kx)[4], int koff, const bf16x8* qr, const f32x16& negm) {
;   lds_b128_ptr k0 = (lds_b128_ptr)(unsigned)(kx[0] + koff), k1 = (lds_b128_ptr)(unsigned)(kx[1] + koff), k2 = (lds_b128_ptr)(unsigned)(kx[2] + koff), k3 = (lds_b128_ptr)(unsigned)(kx[3] + koff);
; #pragma unroll
;   for (int d0 = 0; d0 < DQ / 16; ++d0) { lds_b128_ptr kp = (d0 & 3) == 0 ? k0 : (d0 & 3) == 1 ? k1 : (d0 & 3) == 2 ? k2 : k3;
;     const bf16x8 b0 = kp[(d0 >> 2) * 8];
;     const bf16x8 b1 = kp[(d0 >> 2) * 8 + 32 * DQ * 2 / 16];
;     if (d0 == 0) { p0 = __builtin_amdgcn_mfma_f32_32x32x16_bf16(b0, qr[0], negm, 0, 0, 0); p1 = __builtin_amdgcn_mfma_f32_32x32x16_bf16(b1, qr[0], negm, 0, 0, 0); }
;     else { p0 = __builtin_amdgcn_mfma_f32_32x32x16_bf16(b0, qr[d0], p0, 0, 0, 0); p1 = __builtin_amdgcn_mfma_f32_32x32x16_bf16(b1, qr[d0], p1, 0, 0, 0); } }
; template <int DQ, int MODE>
; __device__ __forceinline__ void attn_unit(const Args& a, char* lds, const int wave0) {
;     ...
;   f32x16 pA0, pA1, pB0, pB1; float mnA, mnB, alA, alB; bf16x8 pa0, pa1, pa2, pa3; const int NT = a.NT;
.LBB0_776:
	s_waitcnt vmcnt(0) lgkmcnt(0)
	s_barrier
	s_add_i32 s4, s4, 1
	s_cmp_ge_u32 s4, s62
	s_cbranch_scc1 .LBB0_778
	s_cmp_lt_u32 s93, 0x100
	s_cbranch_scc0 .LBB0_778
	s_mul_hi_u32 s5, s46, 0xaaaaaaab
	s_lshr_b32 s5, s5, 1
	s_mul_i32 s5, s5, 0xc000
	s_cmp_lt_u32 s47, 2
	v_subrev_u32_e32 v80, s5, v189
	s_cselect_b32 s5, 0, -4
	s_cselect_b32 s6, s20, s63
	s_add_i32 s5, s5, s47
	s_lshl_b32 s5, s5, 6
	s_add_i32 s5, s5, s6
	s_addk_i32 s5, 0x80
	s_cmp_lg_u32 0, -1
	v_readfirstlane_b32 s6, v179
	s_cselect_b32 s7, 0, 0
	s_add_i32 s8, s7, s6
	s_add_i32 s9, s8, 0x10000
	s_mul_hi_i32 s40, s5, 0x1600
	s_mulk_i32 s5, 0x1600
	s_add_u32 s6, s21, s5
	v_add_u32_e32 v82, s7, v80
	s_addc_u32 s7, s43, s40
	v_lshl_add_u64 v[80:81], v[162:163], 1, s[6:7]
	s_mov_b32 s41, m0
	s_mov_b32 m0, s9
	s_nop 0
	global_load_lds_dwordx4 v[80:81], off
	s_mov_b32 m0, s41
	v_lshl_add_u64 v[80:81], v[164:165], 1, s[6:7]
	s_add_i32 s8, s8, 0x10400
	s_mov_b32 s6, m0
	s_mov_b32 m0, s8
	s_nop 0
	global_load_lds_dwordx4 v[80:81], off
	s_mov_b32 m0, s6
	s_add_u32 s6, s44, s5
	s_addc_u32 s7, s45, s40
	v_readfirstlane_b32 s8, v82
	v_lshl_add_u64 v[80:81], v[166:167], 1, s[6:7]
	s_mov_b32 s5, m0
	s_mov_b32 m0, s8
	s_nop 0
	global_load_lds_dwordx4 v[80:81], off
	s_mov_b32 m0, s5
	v_lshl_add_u64 v[80:81], v[80:81], 0, s[22:23]
	s_add_i32 s5, s8, 0x400
	s_mov_b32 s6, m0
	s_mov_b32 m0, s5
	s_nop 0
	global_load_lds_dwordx4 v[80:81], off
	s_mov_b32 m0, s6
.LBB0_778:
	v_exp_f32_e32 v193, v112
	s_mul_hi_u32 s5, s47, 0xaaaaaaab
	s_lshr_b32 s5, s5, 1
	s_mul_i32 s5, s5, 0xc000
	v_exp_f32_e32 v197, v113
	v_exp_f32_e32 v203, v114
	v_exp_f32_e32 v208, v115
	v_exp_f32_e32 v209, v116
	v_exp_f32_e32 v210, v117
	v_exp_f32_e32 v216, v118
	v_exp_f32_e32 v217, v119
	v_exp_f32_e32 v218, v120
	v_exp_f32_e32 v219, v121
	v_exp_f32_e32 v220, v122
	v_exp_f32_e32 v221, v123
	v_exp_f32_e32 v222, v124
	v_exp_f32_e32 v223, v125
	v_exp_f32_e32 v224, v126
	v_exp_f32_e32 v225, v127
	v_subrev_u32_e32 v226, s5, v188
	ds_read_b128 v[204:207], v176 offset:8192
	ds_read_b128 v[80:83], v176
	v_exp_f32_e32 v227, v104
	v_exp_f32_e32 v228, v105
	v_exp_f32_e32 v229, v106
	v_exp_f32_e32 v230, v107
	s_waitcnt lgkmcnt(0)
	v_mfma_f32_32x32x16_bf16 v[112:127], v[80:83], v[144:147], v[64:79]
	v_exp_f32_e32 v231, v108
	v_exp_f32_e32 v232, v109
	v_exp_f32_e32 v110, v110
	v_exp_f32_e32 v111, v111
	v_mfma_f32_32x32x16_bf16 v[80:95], v[204:207], v[144:147], v[64:79]
	ds_read_b128 v[204:207], v181 offset:8192
	ds_read_b128 v[212:215], v181
	s_waitcnt lgkmcnt(1)
	v_mfma_f32_32x32x16_bf16 v[80:95], v[204:207], v[152:155], v[80:95]
	s_waitcnt lgkmcnt(0)
	v_mfma_f32_32x32x16_bf16 v[112:127], v[212:215], v[152:155], v[112:127]
	ds_read_b128 v[204:207], v178 offset:8192
	ds_read_b128 v[212:215], v178
	s_waitcnt lgkmcnt(1)
	v_mfma_f32_32x32x16_bf16 v[80:95], v[204:207], v[148:151], v[80:95]
	s_waitcnt lgkmcnt(0)
	v_mfma_f32_32x32x16_bf16 v[112:127], v[212:215], v[148:151], v[112:127]
	ds_read_b128 v[204:207], v177 offset:8192
	ds_read_b128 v[212:215], v177
	s_waitcnt lgkmcnt(1)
	v_mfma_f32_32x32x16_bf16 v[80:95], v[204:207], v[156:159], v[80:95]
	s_waitcnt lgkmcnt(0)
	v_mfma_f32_32x32x16_bf16 v[112:127], v[212:215], v[156:159], v[112:127]
	ds_read_b128 v[204:207], v176 offset:8320
	ds_read_b128 v[212:215], v176 offset:128
	s_waitcnt lgkmcnt(1)
	v_mfma_f32_32x32x16_bf16 v[80:95], v[204:207], v[140:143], v[80:95]
	s_waitcnt lgkmcnt(0)
	v_mfma_f32_32x32x16_bf16 v[112:127], v[212:215], v[140:143], v[112:127]
	ds_read_b128 v[204:207], v181 offset:8320
	ds_read_b128 v[212:215], v181 offset:128
	s_waitcnt lgkmcnt(1)
	v_mfma_f32_32x32x16_bf16 v[80:95], v[204:207], v[132:135], v[80:95]
	s_waitcnt lgkmcnt(0)
	v_mfma_f32_32x32x16_bf16 v[112:127], v[212:215], v[132:135], v[112:127]
	ds_read_b128 v[204:207], v178 offset:8320
	ds_read_b128 v[212:215], v178 offset:128
	s_waitcnt lgkmcnt(1)
	v_mfma_f32_32x32x16_bf16 v[80:95], v[204:207], v[136:139], v[80:95]
	s_waitcnt lgkmcnt(0)
	v_mfma_f32_32x32x16_bf16 v[112:127], v[212:215], v[136:139], v[112:127]
	ds_read_b128 v[204:207], v177 offset:8320
	ds_read_b128 v[212:215], v177 offset:128
	s_waitcnt lgkmcnt(1)
	v_mfma_f32_32x32x16_bf16 v[80:95], v[204:207], v[128:131], v[80:95]
	v_exp_f32_e32 v204, v96
	v_add_f32_e32 v96, 0, v193
	v_add_f32_e32 v96, v197, v96
	v_add_f32_e32 v96, v203, v96
	v_add_f32_e32 v96, v208, v96
	v_add_f32_e32 v96, v209, v96
	v_add_f32_e32 v96, v210, v96
	v_add_f32_e32 v96, v216, v96
	v_add_f32_e32 v96, v217, v96
	v_add_f32_e32 v96, v218, v96
	v_add_f32_e32 v96, v219, v96
	v_add_f32_e32 v96, v220, v96
	v_add_f32_e32 v96, v221, v96
	v_add_f32_e32 v96, v222, v96
	v_exp_f32_e32 v205, v97
	v_add_f32_e32 v96, v223, v96
	v_exp_f32_e32 v206, v98
	v_add_f32_e32 v96, v224, v96
	v_exp_f32_e32 v207, v99
	v_add_f32_e32 v96, v225, v96
	s_waitcnt lgkmcnt(0)
	v_mfma_f32_32x32x16_bf16 v[112:127], v[212:215], v[128:131], v[112:127]
	v_exp_f32_e32 v212, v100
	v_add_f32_e32 v96, v204, v96
	v_exp_f32_e32 v213, v101
	v_add_f32_e32 v96, v205, v96
	v_exp_f32_e32 v214, v102
	v_add_f32_e32 v96, v206, v96
	v_exp_f32_e32 v215, v103
	v_add_f32_e32 v96, v207, v96
	v_add_f32_e32 v96, v212, v96
	v_add_f32_e32 v96, v213, v96
	v_add_f32_e32 v96, v214, v96
	v_add_f32_e32 v96, v215, v96
	v_add_f32_e32 v96, v227, v96
	v_add_f32_e32 v96, v228, v96
	v_add_f32_e32 v96, v229, v96
	v_add_f32_e32 v96, v230, v96
	v_add_f32_e32 v96, v231, v96
	v_add_f32_e32 v96, v232, v96
	v_add_f32_e32 v96, v110, v96
	v_add_f32_e32 v96, v111, v96
	v_mov_b32_e32 v97, v96
	s_nop 1
	v_permlane32_swap_b32_e32 v96, v97
	v_cvt_pk_bf16_f32 v98, v193, v197
	v_cvt_pk_bf16_f32 v99, v203, v208
	v_cvt_pk_bf16_f32 v100, v209, v210
	v_cvt_pk_bf16_f32 v101, v216, v217
	v_cvt_pk_bf16_f32 v102, v218, v219
	v_cvt_pk_bf16_f32 v103, v220, v221
	v_cvt_pk_bf16_f32 v104, v222, v223
	v_cvt_pk_bf16_f32 v105, v224, v225
	v_cvt_pk_bf16_f32 v106, v204, v205
	v_cvt_pk_bf16_f32 v107, v206, v207
	v_cvt_pk_bf16_f32 v108, v212, v213
	v_cvt_pk_bf16_f32 v109, v214, v215
	v_cvt_pk_bf16_f32 v204, v227, v228
	v_cvt_pk_bf16_f32 v205, v229, v230
	v_cvt_pk_bf16_f32 v206, v231, v232
	v_cvt_pk_bf16_f32 v207, v110, v111
	s_cmp_lt_u32 s93, 0x100
	s_cbranch_scc1 .Ldma2b_skip_128
; #define SBAR() __builtin_amdgcn_sched_barrier(0)
; template <int D0> __device__ __forceinline__ void pv_one(f32x16& od, int vb, bf16x8 pa0, bf16x8 pa1, bf16x8 pa2, bf16x8 pa3) {
;   const s16x4 l0 = tr_read<v_rd_off(D0, 0, 0)>(vb), h0 = tr_read<v_rd_off(D0, 0, 1)>(vb), l1 = tr_read<v_rd_off(D0, 1, 0)>(vb), h1 = tr_read<v_rd_off(D0, 1, 1)>(vb);
;   const s16x4 l2 = tr_read<v_rd_off(D0, 2, 0)>(vb), h2 = tr_read<v_rd_off(D0, 2, 1)>(vb), l3 = tr_read<v_rd_off(D0, 3, 0)>(vb), h3 = tr_read<v_rd_off(D0, 3, 1)>(vb);
;   asm volatile("s_waitcnt lgkmcnt(0)" ::: "memory"); SBAR();
;     ...
;   od = __builtin_amdgcn_mfma_f32_32x32x16_bf16(pa0, PK(l0, h0), od, 0, 0, 0);
;   od = __builtin_amdgcn_mfma_f32_32x32x16_bf16(pa1, PK(l1, h1), od, 0, 0, 0);
;   od = __builtin_amdgcn_mfma_f32_32x32x16_bf16(pa2, PK(l2, h2), od, 0, 0, 0);
;   od = __builtin_amdgcn_mfma_f32_32x32x16_bf16(pa3, PK(l3, h3), od, 0, 0, 0);
;     ...
; }
; __device__ __forceinline__ void pv_d0(f32x16* o, int vb, bf16x8 pa0, bf16x8 pa1, bf16x8 pa2, bf16x8 pa3) {
;   pv_one<0>(o[0], vb, pa0, pa1, pa2, pa3); pv_one<1>(o[1], vb, pa0, pa1, pa2, pa3); pv_one<2>(o[2], vb, pa0, pa1, pa2, pa3); pv_one<3>(o[3], vb, pa0, pa1, pa2, pa3);
; }
	s_cmp_ge_u32 s4, s62
	s_cbranch_scc1 .Ldma2b_skip_128
	s_mul_hi_u32 s5, s46, 0xaaaaaaab
	s_lshr_b32 s5, s5, 1
	s_mul_i32 s5, s5, 0xc000
	s_cmp_lt_u32 s47, 2
	v_subrev_u32_e32 v248, s5, v189
	s_cselect_b32 s5, 0, -4
	s_cselect_b32 s6, s20, s63
	s_add_i32 s5, s5, s47
	s_lshl_b32 s5, s5, 6
	s_add_i32 s5, s5, s6
	s_addk_i32 s5, 0x80
	s_cmp_lg_u32 0, -1
	v_readfirstlane_b32 s6, v179
	s_cselect_b32 s7, 0, 0
	s_add_i32 s8, s7, s6
	s_add_i32 s9, s8, 0x10000
	s_mul_hi_i32 s40, s5, 0x1600
	s_mulk_i32 s5, 0x1600
	s_add_u32 s6, s21, s5
	v_add_u32_e32 v233, s7, v248
	s_addc_u32 s7, s43, s40
	v_lshl_add_u64 v[246:247], v[162:163], 1, s[6:7]
	s_mov_b32 m0, s9
	s_nop 0
	global_load_lds_dwordx4 v[246:247], off
	v_lshl_add_u64 v[246:247], v[164:165], 1, s[6:7]
	s_add_i32 s8, s8, 0x10400
	s_mov_b32 m0, s8
	s_nop 0
	global_load_lds_dwordx4 v[246:247], off
	s_add_u32 s6, s44, s5
	s_addc_u32 s7, s45, s40
	v_readfirstlane_b32 s8, v233
	v_lshl_add_u64 v[246:247], v[166:167], 1, s[6:7]
	s_mov_b32 m0, s8
	s_nop 0
	global_load_lds_dwordx4 v[246:247], off
	v_lshl_add_u64 v[246:247], v[246:247], 0, s[22:23]
	s_add_i32 s5, s8, 0x400
	s_mov_b32 m0, s5
	s_nop 0
	global_load_lds_dwordx4 v[246:247], off
.Ldma2b_skip_128:
	s_cmp_lg_u32 0, -1
	s_cselect_b32 s5, 0, 0
	v_add_u32_e32 v110, s5, v226
	ds_read_b64_tr_b16 v[212:213], v110 offset:0
	ds_read_b64_tr_b16 v[214:215], v110 offset:0x800
	ds_read_b64_tr_b16 v[216:217], v110 offset:0x1000
	ds_read_b64_tr_b16 v[218:219], v110 offset:0x1800
	ds_read_b64_tr_b16 v[220:221], v110 offset:0x2000
	ds_read_b64_tr_b16 v[222:223], v110 offset:0x2800
	ds_read_b64_tr_b16 v[224:225], v110 offset:0x3000
	ds_read_b64_tr_b16 v[226:227], v110 offset:0x3800
	s_waitcnt lgkmcnt(0)
	s_nop 0
	v_mfma_f32_32x32x16_bf16 v[0:15], v[98:101], v[212:215], v[0:15]
	ds_read_b64_tr_b16 v[212:213], v110 offset:0x200
	ds_read_b64_tr_b16 v[214:215], v110 offset:0xa00
	v_mfma_f32_32x32x16_bf16 v[0:15], v[102:105], v[216:219], v[0:15]
	ds_read_b64_tr_b16 v[216:217], v110 offset:0x1200
	ds_read_b64_tr_b16 v[218:219], v110 offset:0x1a00
	v_mfma_f32_32x32x16_bf16 v[0:15], v[106:109], v[220:223], v[0:15]
	ds_read_b64_tr_b16 v[220:221], v110 offset:0x2200
	ds_read_b64_tr_b16 v[222:223], v110 offset:0x2a00
	v_mfma_f32_32x32x16_bf16 v[0:15], v[204:207], v[224:227], v[0:15]
	ds_read_b64_tr_b16 v[224:225], v110 offset:0x3200
	ds_read_b64_tr_b16 v[226:227], v110 offset:0x3a00
	s_waitcnt lgkmcnt(0)
	v_mfma_f32_32x32x16_bf16 v[48:63], v[98:101], v[212:215], v[48:63]
	ds_read_b64_tr_b16 v[212:213], v110 offset:0x400
	ds_read_b64_tr_b16 v[214:215], v110 offset:0xc00
	v_mfma_f32_32x32x16_bf16 v[48:63], v[102:105], v[216:219], v[48:63]
	ds_read_b64_tr_b16 v[216:217], v110 offset:0x1400
	ds_read_b64_tr_b16 v[218:219], v110 offset:0x1c00
	v_mfma_f32_32x32x16_bf16 v[48:63], v[106:109], v[220:223], v[48:63]
	ds_read_b64_tr_b16 v[220:221], v110 offset:0x2400
	ds_read_b64_tr_b16 v[222:223], v110 offset:0x2c00
	v_mfma_f32_32x32x16_bf16 v[48:63], v[204:207], v[224:227], v[48:63]
	ds_read_b64_tr_b16 v[224:225], v110 offset:0x3400
	ds_read_b64_tr_b16 v[226:227], v110 offset:0x3c00
	s_waitcnt lgkmcnt(0)
	v_mfma_f32_32x32x16_bf16 v[32:47], v[98:101], v[212:215], v[32:47]
	ds_read_b64_tr_b16 v[212:213], v110 offset:0x600
	ds_read_b64_tr_b16 v[214:215], v110 offset:0xe00
	v_mfma_f32_32x32x16_bf16 v[32:47], v[102:105], v[216:219], v[32:47]
	ds_read_b64_tr_b16 v[216:217], v110 offset:0x1600
	ds_read_b64_tr_b16 v[218:219], v110 offset:0x1e00
	v_mfma_f32_32x32x16_bf16 v[32:47], v[106:109], v[220:223], v[32:47]
	ds_read_b64_tr_b16 v[220:221], v110 offset:0x2600
	ds_read_b64_tr_b16 v[222:223], v110 offset:0x2e00
	v_mfma_f32_32x32x16_bf16 v[32:47], v[204:207], v[224:227], v[32:47]
	ds_read_b64_tr_b16 v[224:225], v110 offset:0x3600
	ds_read_b64_tr_b16 v[226:227], v110 offset:0x3e00
	s_waitcnt lgkmcnt(0)
	v_mfma_f32_32x32x16_bf16 v[16:31], v[98:101], v[212:215], v[16:31]
	v_max_f32_e32 v98, v113, v113
	v_max_f32_e32 v99, v112, v112
	v_max_f32_e32 v98, v99, v98
	v_max3_f32 v98, v98, v114, v115
	v_max3_f32 v98, v98, v116, v117
	v_max3_f32 v98, v98, v118, v119
	v_max3_f32 v98, v98, v120, v121
	v_mfma_f32_32x32x16_bf16 v[16:31], v[102:105], v[216:219], v[16:31]
	v_max3_f32 v98, v98, v122, v123
	v_max3_f32 v98, v98, v124, v125
	v_max3_f32 v98, v98, v126, v127
	v_max3_f32 v98, v98, v80, v81
	v_max3_f32 v98, v98, v82, v83
	v_max3_f32 v98, v98, v84, v85
	v_max3_f32 v98, v98, v86, v87
	v_mfma_f32_32x32x16_bf16 v[16:31], v[106:109], v[220:223], v[16:31]
	v_max3_f32 v98, v98, v88, v89
	v_max3_f32 v98, v98, v90, v91
	v_max3_f32 v98, v98, v92, v93
	v_max3_f32 v98, v98, v94, v95
	v_mov_b32_e32 v99, v98
	s_nop 1
	v_permlane32_swap_b32_e32 v98, v99
	v_mfma_f32_32x32x16_bf16 v[16:31], v[204:207], v[224:227], v[16:31]
	v_max_f32_e32 v99, v99, v99
	v_max_f32_e32 v98, v98, v98
	v_max_f32_e32 v98, v98, v99
	v_cmp_ge_f32_e32 vcc, s81, v98
	s_cmp_eq_u64 vcc, exec
	v_mov_b32_e32 v193, 1.0
	s_cbranch_scc0 .LBB0_786
	v_cmp_gt_f32_e32 vcc, 1.0, v193
	s_cbranch_vccz .LBB0_783
